# L0 out-proj epilogue: second residual half (offset 512/528) loaded together with the first half instead of after its stores; counted waits
# baseline (speedup 1.0000x reference)
.LBB0_862:
	v_mov_b32_e32 v3, v0
	s_lshl_b32 s4, s65, 8
	v_and_or_b32 v134, v3, 15, s53
	v_ashrrev_i32_e32 v135, 31, v134
	v_lshlrev_b64 v[4:5], 6, v[134:135]
	v_lshl_add_u64 v[4:5], s[26:27], 0, v[4:5]
	global_load_dwordx4 v[136:139], v[4:5], off offset:32
	global_load_dwordx4 v[140:143], v[4:5], off offset:48
	v_lshrrev_b32_e32 v3, 1, v3
	v_and_or_b32 v3, v3, 24, s4
	v_or_b32_e32 v4, s47, v3
	v_lshlrev_b64 v[144:145], 11, v[134:135]
	v_ashrrev_i32_e32 v5, 31, v4
	v_lshl_add_u64 v[144:145], v[144:145], 0, v[4:5]
	v_readlane_b32 s76, v254, 14
	v_lshlrev_b64 v[148:149], 2, v[144:145]
	v_readlane_b32 s77, v254, 15
	v_readlane_b32 s78, v254, 16
	v_readlane_b32 s79, v254, 17
	v_lshl_add_u64 v[160:161], s[76:77], 0, v[148:149]
	global_load_dwordx4 v[144:147], v[160:161], off
	global_load_dwordx4 v[166:169], v[160:161], off offset:16
	global_load_dwordx4 v[170:173], v[160:161], off offset:512
	global_load_dwordx4 v[174:177], v[160:161], off offset:528
	v_readlane_b32 s80, v254, 18
	v_readlane_b32 s81, v254, 19
	v_readlane_b32 s82, v254, 20
	v_readlane_b32 s83, v254, 21
	v_readlane_b32 s84, v254, 22
	v_readlane_b32 s85, v254, 23
	v_readlane_b32 s86, v254, 24
	v_readlane_b32 s87, v254, 25
	v_readlane_b32 s88, v254, 26
	v_readlane_b32 s89, v254, 27
	v_readlane_b32 s90, v254, 28
	v_readlane_b32 s91, v254, 29
	s_waitcnt vmcnt(2)
	v_pk_add_f32 v[138:139], v[138:139], v[142:143]
	v_pk_add_f32 v[136:137], v[136:137], v[140:141]
	s_nop 0
	v_pk_mov_b32 v[140:141], v[136:137], v[138:139] op_sel:[1,0]
	v_mov_b32_e32 v137, v139
	v_pk_add_f32 v[136:137], v[140:141], v[136:137]
	s_nop 0
	v_add_f32_e32 v3, v136, v137
	v_fmamk_f32 v3, v3, 0x3a800000, v164
	v_mul_f32_e32 v135, 0x4f800000, v3
	v_cmp_gt_f32_e32 vcc, s50, v3
	s_nop 1
	v_cndmask_b32_e32 v3, v3, v135, vcc
	v_sqrt_f32_e32 v135, v3
	s_nop 0
	v_add_u32_e32 v136, -1, v135
	v_add_u32_e32 v137, 1, v135
	v_fma_f32 v138, -v136, v135, v3
	v_fma_f32 v139, -v137, v135, v3
	v_cmp_ge_f32_e64 s[8:9], 0, v138
	s_nop 1
	v_cndmask_b32_e64 v135, v135, v136, s[8:9]
	v_cmp_lt_f32_e64 s[8:9], 0, v139
	s_nop 1
	v_cndmask_b32_e64 v135, v135, v137, s[8:9]
	v_mul_f32_e32 v136, 0x37800000, v135
	v_cndmask_b32_e32 v135, v135, v136, vcc
	v_cmp_class_f32_e32 vcc, v3, v162
	v_lshl_add_u64 v[136:137], s[22:23], 0, v[148:149]
	v_or_b32_e32 v148, 0x200, v148
	v_cndmask_b32_e32 v3, v135, v3, vcc
	v_div_scale_f32 v135, s[4:5], v3, v3, 1.0
	v_rcp_f32_e32 v138, v135
	v_div_scale_f32 v139, vcc, 1.0, v3, 1.0
	v_fma_f32 v140, -v135, v138, 1.0
	v_fmac_f32_e32 v138, v140, v138
	v_mul_f32_e32 v140, v139, v138
	v_fma_f32 v141, -v135, v140, v139
	v_fmac_f32_e32 v140, v141, v138
	v_fma_f32 v135, -v135, v140, v139
	v_div_fmas_f32 v135, v135, v138, v140
	v_div_fixup_f32 v138, v135, v3, 1.0
	v_pk_mul_f32 v[130:131], v[130:131], v[138:139] op_sel_hi:[1,0]
	v_pk_mul_f32 v[132:133], v[132:133], v[138:139] op_sel_hi:[1,0]
	v_pk_mul_f32 v[140:141], v[126:127], v[138:139] op_sel_hi:[1,0]
	v_pk_mul_f32 v[142:143], v[128:129], v[138:139] op_sel_hi:[1,0]
	v_pk_fma_f32 v[128:129], v[146:147], s[48:49], v[132:133] op_sel_hi:[1,0,1]
	v_pk_fma_f32 v[126:127], v[144:145], s[48:49], v[130:131] op_sel_hi:[1,0,1]
	v_pk_fma_f32 v[132:133], v[168:169], s[48:49], v[142:143] op_sel_hi:[1,0,1]
	v_pk_fma_f32 v[130:131], v[166:167], s[48:49], v[140:141] op_sel_hi:[1,0,1]
	global_store_dwordx4 v[136:137], v[126:129], off
	global_store_dwordx4 v[136:137], v[130:133], off offset:16
	v_or_b32_e32 v136, 16, v134
	v_pk_mul_f32 v[124:125], v[124:125], v[138:139] op_sel_hi:[1,0]
	v_pk_mul_f32 v[122:123], v[122:123], v[138:139] op_sel_hi:[1,0]
	v_ashrrev_i32_e32 v137, 31, v136
	v_lshl_add_u64 v[142:143], s[22:23], 0, v[148:149]
	v_pk_mul_f32 v[144:145], v[120:121], v[138:139] op_sel_hi:[1,0]
	v_pk_mul_f32 v[138:139], v[118:119], v[138:139] op_sel_hi:[1,0]
	v_lshlrev_b64 v[140:141], 6, v[136:137]
	v_lshl_add_u64 v[140:141], s[26:27], 0, v[140:141]
	s_waitcnt vmcnt(3)
	v_pk_fma_f32 v[118:119], v[170:171], s[48:49], v[122:123] op_sel_hi:[1,0,1]
	v_pk_fma_f32 v[120:121], v[172:173], s[48:49], v[124:125] op_sel_hi:[1,0,1]
	s_waitcnt vmcnt(2)
	v_pk_fma_f32 v[122:123], v[174:175], s[48:49], v[138:139] op_sel_hi:[1,0,1]
	v_pk_fma_f32 v[124:125], v[176:177], s[48:49], v[144:145] op_sel_hi:[1,0,1]
	global_store_dwordx4 v[142:143], v[118:121], off
	global_store_dwordx4 v[142:143], v[122:125], off offset:16
	global_load_dwordx4 v[118:121], v[140:141], off offset:32
	global_load_dwordx4 v[122:125], v[140:141], off offset:48
	v_lshlrev_b64 v[126:127], 11, v[136:137]
	v_lshl_add_u64 v[126:127], v[126:127], 0, v[4:5]
	v_lshlrev_b64 v[136:137], 2, v[126:127]
	v_lshl_add_u64 v[138:139], s[76:77], 0, v[136:137]
	global_load_dwordx4 v[126:129], v[138:139], off
	global_load_dwordx4 v[130:133], v[138:139], off offset:16
	global_load_dwordx4 v[170:173], v[138:139], off offset:512
	global_load_dwordx4 v[174:177], v[138:139], off offset:528
	s_waitcnt vmcnt(4)
	v_pk_add_f32 v[120:121], v[120:121], v[124:125]
	v_pk_add_f32 v[118:119], v[118:119], v[122:123]
	s_nop 0
	v_pk_mov_b32 v[122:123], v[118:119], v[120:121] op_sel:[1,0]
	v_mov_b32_e32 v119, v121
	v_pk_add_f32 v[118:119], v[122:123], v[118:119]
	s_nop 0
	v_add_f32_e32 v3, v118, v119
	v_fmamk_f32 v3, v3, 0x3a800000, v164
	v_mul_f32_e32 v118, 0x4f800000, v3
	v_cmp_gt_f32_e32 vcc, s50, v3
	s_nop 1
	v_cndmask_b32_e32 v3, v3, v118, vcc
	v_sqrt_f32_e32 v118, v3
	s_nop 0
	v_add_u32_e32 v119, -1, v118
	v_add_u32_e32 v120, 1, v118
	v_fma_f32 v121, -v119, v118, v3
	v_fma_f32 v122, -v120, v118, v3
	v_cmp_ge_f32_e64 s[8:9], 0, v121
	s_nop 1
	v_cndmask_b32_e64 v118, v118, v119, s[8:9]
	v_cmp_lt_f32_e64 s[8:9], 0, v122
	s_nop 1
	v_cndmask_b32_e64 v118, v118, v120, s[8:9]
	v_mul_f32_e32 v119, 0x37800000, v118
	v_cndmask_b32_e32 v118, v118, v119, vcc
	v_cmp_class_f32_e32 vcc, v3, v162
	s_nop 1
	v_cndmask_b32_e32 v3, v118, v3, vcc
	v_div_scale_f32 v120, s[4:5], v3, v3, 1.0
	v_rcp_f32_e32 v121, v120
	v_div_scale_f32 v122, vcc, 1.0, v3, 1.0
	v_lshl_add_u64 v[118:119], s[22:23], 0, v[136:137]
	v_fma_f32 v123, -v120, v121, 1.0
	v_fmac_f32_e32 v121, v123, v121
	v_mul_f32_e32 v123, v122, v121
	v_fma_f32 v124, -v120, v123, v122
	v_fmac_f32_e32 v123, v124, v121
	v_fma_f32 v120, -v120, v123, v122
	v_div_fmas_f32 v120, v120, v121, v123
	v_div_fixup_f32 v120, v120, v3, 1.0
	v_pk_mul_f32 v[114:115], v[114:115], v[120:121] op_sel_hi:[1,0]
	v_pk_mul_f32 v[116:117], v[116:117], v[120:121] op_sel_hi:[1,0]
	v_pk_mul_f32 v[122:123], v[110:111], v[120:121] op_sel_hi:[1,0]
	v_pk_mul_f32 v[124:125], v[112:113], v[120:121] op_sel_hi:[1,0]
	s_waitcnt vmcnt(3)
	v_pk_fma_f32 v[112:113], v[128:129], s[48:49], v[116:117] op_sel_hi:[1,0,1]
	v_pk_fma_f32 v[110:111], v[126:127], s[48:49], v[114:115] op_sel_hi:[1,0,1]
	s_waitcnt vmcnt(2)
	v_pk_fma_f32 v[116:117], v[132:133], s[48:49], v[124:125] op_sel_hi:[1,0,1]
	v_pk_fma_f32 v[114:115], v[130:131], s[48:49], v[122:123] op_sel_hi:[1,0,1]
	global_store_dwordx4 v[118:119], v[110:113], off
	global_store_dwordx4 v[118:119], v[114:117], off offset:16
	v_or_b32_e32 v118, 32, v134
	v_or_b32_e32 v136, 0x200, v136
	v_pk_mul_f32 v[108:109], v[108:109], v[120:121] op_sel_hi:[1,0]
	v_pk_mul_f32 v[106:107], v[106:107], v[120:121] op_sel_hi:[1,0]
	v_ashrrev_i32_e32 v119, 31, v118
	v_lshl_add_u64 v[124:125], s[22:23], 0, v[136:137]
	v_pk_mul_f32 v[126:127], v[104:105], v[120:121] op_sel_hi:[1,0]
	v_pk_mul_f32 v[120:121], v[102:103], v[120:121] op_sel_hi:[1,0]
	v_lshlrev_b64 v[122:123], 6, v[118:119]
	v_lshl_add_u64 v[122:123], s[26:27], 0, v[122:123]
	s_waitcnt vmcnt(3)
	v_pk_fma_f32 v[102:103], v[170:171], s[48:49], v[106:107] op_sel_hi:[1,0,1]
	v_pk_fma_f32 v[104:105], v[172:173], s[48:49], v[108:109] op_sel_hi:[1,0,1]
	s_waitcnt vmcnt(2)
	v_pk_fma_f32 v[106:107], v[174:175], s[48:49], v[120:121] op_sel_hi:[1,0,1]
	v_pk_fma_f32 v[108:109], v[176:177], s[48:49], v[126:127] op_sel_hi:[1,0,1]
	global_store_dwordx4 v[124:125], v[102:105], off
	global_store_dwordx4 v[124:125], v[106:109], off offset:16
	global_load_dwordx4 v[102:105], v[122:123], off offset:32
	global_load_dwordx4 v[106:109], v[122:123], off offset:48
	v_lshlrev_b64 v[110:111], 11, v[118:119]
	v_lshl_add_u64 v[110:111], v[110:111], 0, v[4:5]
	v_lshlrev_b64 v[118:119], 2, v[110:111]
	v_lshl_add_u64 v[120:121], s[76:77], 0, v[118:119]
	global_load_dwordx4 v[110:113], v[120:121], off
	global_load_dwordx4 v[114:117], v[120:121], off offset:16
	global_load_dwordx4 v[170:173], v[120:121], off offset:512
	global_load_dwordx4 v[174:177], v[120:121], off offset:528
	s_waitcnt vmcnt(4)
	v_pk_add_f32 v[104:105], v[104:105], v[108:109]
	v_pk_add_f32 v[102:103], v[102:103], v[106:107]
	s_nop 0
	v_pk_mov_b32 v[106:107], v[102:103], v[104:105] op_sel:[1,0]
	v_mov_b32_e32 v103, v105
	v_pk_add_f32 v[102:103], v[106:107], v[102:103]
	s_nop 0
	v_add_f32_e32 v3, v102, v103
	v_fmamk_f32 v3, v3, 0x3a800000, v164
	v_mul_f32_e32 v102, 0x4f800000, v3
	v_cmp_gt_f32_e32 vcc, s50, v3
	s_nop 1
	v_cndmask_b32_e32 v3, v3, v102, vcc
	v_sqrt_f32_e32 v102, v3
	s_nop 0
	v_add_u32_e32 v103, -1, v102
	v_add_u32_e32 v104, 1, v102
	v_fma_f32 v105, -v103, v102, v3
	v_fma_f32 v106, -v104, v102, v3
	v_cmp_ge_f32_e64 s[8:9], 0, v105
	s_nop 1
	v_cndmask_b32_e64 v102, v102, v103, s[8:9]
	v_cmp_lt_f32_e64 s[8:9], 0, v106
	s_nop 1
	v_cndmask_b32_e64 v102, v102, v104, s[8:9]
	v_mul_f32_e32 v103, 0x37800000, v102
	v_cndmask_b32_e32 v102, v102, v103, vcc
	v_cmp_class_f32_e32 vcc, v3, v162
	s_nop 1
	v_cndmask_b32_e32 v3, v102, v3, vcc
	v_div_scale_f32 v104, s[4:5], v3, v3, 1.0
	v_rcp_f32_e32 v105, v104
	v_div_scale_f32 v106, vcc, 1.0, v3, 1.0
	v_lshl_add_u64 v[102:103], s[22:23], 0, v[118:119]
	v_fma_f32 v107, -v104, v105, 1.0
	v_fmac_f32_e32 v105, v107, v105
	v_mul_f32_e32 v107, v106, v105
	v_fma_f32 v108, -v104, v107, v106
	v_fmac_f32_e32 v107, v108, v105
	v_fma_f32 v104, -v104, v107, v106
	v_div_fmas_f32 v104, v104, v105, v107
	v_div_fixup_f32 v104, v104, v3, 1.0
	v_pk_mul_f32 v[98:99], v[98:99], v[104:105] op_sel_hi:[1,0]
	v_pk_mul_f32 v[100:101], v[100:101], v[104:105] op_sel_hi:[1,0]
	v_pk_mul_f32 v[106:107], v[94:95], v[104:105] op_sel_hi:[1,0]
	v_pk_mul_f32 v[108:109], v[96:97], v[104:105] op_sel_hi:[1,0]
	s_waitcnt vmcnt(3)
	v_pk_fma_f32 v[96:97], v[112:113], s[48:49], v[100:101] op_sel_hi:[1,0,1]
	v_pk_fma_f32 v[94:95], v[110:111], s[48:49], v[98:99] op_sel_hi:[1,0,1]
	s_waitcnt vmcnt(2)
	v_pk_fma_f32 v[100:101], v[116:117], s[48:49], v[108:109] op_sel_hi:[1,0,1]
	v_pk_fma_f32 v[98:99], v[114:115], s[48:49], v[106:107] op_sel_hi:[1,0,1]
	global_store_dwordx4 v[102:103], v[94:97], off
	global_store_dwordx4 v[102:103], v[98:101], off offset:16
	v_or_b32_e32 v102, 48, v134
	v_or_b32_e32 v118, 0x200, v118
	v_pk_mul_f32 v[92:93], v[92:93], v[104:105] op_sel_hi:[1,0]
	v_pk_mul_f32 v[90:91], v[90:91], v[104:105] op_sel_hi:[1,0]
	v_ashrrev_i32_e32 v103, 31, v102
	v_lshl_add_u64 v[108:109], s[22:23], 0, v[118:119]
	v_pk_mul_f32 v[110:111], v[88:89], v[104:105] op_sel_hi:[1,0]
	v_pk_mul_f32 v[104:105], v[86:87], v[104:105] op_sel_hi:[1,0]
	v_lshlrev_b64 v[106:107], 6, v[102:103]
	v_lshl_add_u64 v[106:107], s[26:27], 0, v[106:107]
	s_waitcnt vmcnt(3)
	v_pk_fma_f32 v[86:87], v[170:171], s[48:49], v[90:91] op_sel_hi:[1,0,1]
	v_pk_fma_f32 v[88:89], v[172:173], s[48:49], v[92:93] op_sel_hi:[1,0,1]
	s_waitcnt vmcnt(2)
	v_pk_fma_f32 v[90:91], v[174:175], s[48:49], v[104:105] op_sel_hi:[1,0,1]
	v_pk_fma_f32 v[92:93], v[176:177], s[48:49], v[110:111] op_sel_hi:[1,0,1]
	global_store_dwordx4 v[108:109], v[86:89], off
	global_store_dwordx4 v[108:109], v[90:93], off offset:16
	global_load_dwordx4 v[86:89], v[106:107], off offset:32
	global_load_dwordx4 v[90:93], v[106:107], off offset:48
	v_lshlrev_b64 v[94:95], 11, v[102:103]
	v_lshl_add_u64 v[94:95], v[94:95], 0, v[4:5]
	v_lshlrev_b64 v[102:103], 2, v[94:95]
	v_lshl_add_u64 v[104:105], s[76:77], 0, v[102:103]
	global_load_dwordx4 v[94:97], v[104:105], off
	global_load_dwordx4 v[98:101], v[104:105], off offset:16
	global_load_dwordx4 v[170:173], v[104:105], off offset:512
	global_load_dwordx4 v[174:177], v[104:105], off offset:528
	s_waitcnt vmcnt(4)
	v_pk_add_f32 v[88:89], v[88:89], v[92:93]
	v_pk_add_f32 v[86:87], v[86:87], v[90:91]
	s_nop 0
	v_pk_mov_b32 v[90:91], v[86:87], v[88:89] op_sel:[1,0]
	v_mov_b32_e32 v87, v89
	v_pk_add_f32 v[86:87], v[90:91], v[86:87]
	s_nop 0
	v_add_f32_e32 v3, v86, v87
	v_fmamk_f32 v3, v3, 0x3a800000, v164
	v_mul_f32_e32 v86, 0x4f800000, v3
	v_cmp_gt_f32_e32 vcc, s50, v3
	s_nop 1
	v_cndmask_b32_e32 v3, v3, v86, vcc
	v_sqrt_f32_e32 v86, v3
	s_nop 0
	v_add_u32_e32 v87, -1, v86
	v_add_u32_e32 v88, 1, v86
	v_fma_f32 v89, -v87, v86, v3
	v_fma_f32 v90, -v88, v86, v3
	v_cmp_ge_f32_e64 s[8:9], 0, v89
	s_nop 1
	v_cndmask_b32_e64 v86, v86, v87, s[8:9]
	v_cmp_lt_f32_e64 s[8:9], 0, v90
	s_nop 1
	v_cndmask_b32_e64 v86, v86, v88, s[8:9]
	v_mul_f32_e32 v87, 0x37800000, v86
	v_cndmask_b32_e32 v86, v86, v87, vcc
	v_cmp_class_f32_e32 vcc, v3, v162
	s_nop 1
	v_cndmask_b32_e32 v3, v86, v3, vcc
	v_div_scale_f32 v88, s[4:5], v3, v3, 1.0
	v_rcp_f32_e32 v89, v88
	v_div_scale_f32 v90, vcc, 1.0, v3, 1.0
	v_lshl_add_u64 v[86:87], s[22:23], 0, v[102:103]
	v_fma_f32 v91, -v88, v89, 1.0
	v_fmac_f32_e32 v89, v91, v89
	v_mul_f32_e32 v91, v90, v89
	v_fma_f32 v92, -v88, v91, v90
	v_fmac_f32_e32 v91, v92, v89
	v_fma_f32 v88, -v88, v91, v90
	v_div_fmas_f32 v88, v88, v89, v91
	v_div_fixup_f32 v88, v88, v3, 1.0
	v_pk_mul_f32 v[82:83], v[82:83], v[88:89] op_sel_hi:[1,0]
	v_pk_mul_f32 v[84:85], v[84:85], v[88:89] op_sel_hi:[1,0]
	v_pk_mul_f32 v[90:91], v[78:79], v[88:89] op_sel_hi:[1,0]
	v_pk_mul_f32 v[92:93], v[80:81], v[88:89] op_sel_hi:[1,0]
	s_waitcnt vmcnt(3)
	v_pk_fma_f32 v[80:81], v[96:97], s[48:49], v[84:85] op_sel_hi:[1,0,1]
	v_pk_fma_f32 v[78:79], v[94:95], s[48:49], v[82:83] op_sel_hi:[1,0,1]
	s_waitcnt vmcnt(2)
	v_pk_fma_f32 v[84:85], v[100:101], s[48:49], v[92:93] op_sel_hi:[1,0,1]
	v_pk_fma_f32 v[82:83], v[98:99], s[48:49], v[90:91] op_sel_hi:[1,0,1]
	global_store_dwordx4 v[86:87], v[78:81], off
	global_store_dwordx4 v[86:87], v[82:85], off offset:16
	v_add_u32_e32 v86, 0x80, v134
	v_or_b32_e32 v102, 0x200, v102
	v_pk_mul_f32 v[76:77], v[76:77], v[88:89] op_sel_hi:[1,0]
	v_pk_mul_f32 v[74:75], v[74:75], v[88:89] op_sel_hi:[1,0]
	v_ashrrev_i32_e32 v87, 31, v86
	v_lshl_add_u64 v[92:93], s[22:23], 0, v[102:103]
	v_pk_mul_f32 v[94:95], v[72:73], v[88:89] op_sel_hi:[1,0]
	v_pk_mul_f32 v[88:89], v[70:71], v[88:89] op_sel_hi:[1,0]
	v_lshlrev_b64 v[90:91], 6, v[86:87]
	v_lshl_add_u64 v[90:91], s[26:27], 0, v[90:91]
	s_waitcnt vmcnt(3)
	v_pk_fma_f32 v[70:71], v[170:171], s[48:49], v[74:75] op_sel_hi:[1,0,1]
	v_pk_fma_f32 v[72:73], v[172:173], s[48:49], v[76:77] op_sel_hi:[1,0,1]
	s_waitcnt vmcnt(2)
	v_pk_fma_f32 v[74:75], v[174:175], s[48:49], v[88:89] op_sel_hi:[1,0,1]
	v_pk_fma_f32 v[76:77], v[176:177], s[48:49], v[94:95] op_sel_hi:[1,0,1]
	global_store_dwordx4 v[92:93], v[70:73], off
	global_store_dwordx4 v[92:93], v[74:77], off offset:16
	global_load_dwordx4 v[70:73], v[90:91], off offset:32
	global_load_dwordx4 v[74:77], v[90:91], off offset:48
	v_lshlrev_b64 v[78:79], 11, v[86:87]
	v_lshl_add_u64 v[78:79], v[78:79], 0, v[4:5]
	v_lshlrev_b64 v[86:87], 2, v[78:79]
	v_lshl_add_u64 v[88:89], s[76:77], 0, v[86:87]
	global_load_dwordx4 v[78:81], v[88:89], off
	global_load_dwordx4 v[82:85], v[88:89], off offset:16
	global_load_dwordx4 v[170:173], v[88:89], off offset:512
	global_load_dwordx4 v[174:177], v[88:89], off offset:528
	s_waitcnt vmcnt(4)
	v_pk_add_f32 v[72:73], v[72:73], v[76:77]
	v_pk_add_f32 v[70:71], v[70:71], v[74:75]
	s_nop 0
	v_pk_mov_b32 v[74:75], v[70:71], v[72:73] op_sel:[1,0]
	v_mov_b32_e32 v71, v73
	v_pk_add_f32 v[70:71], v[74:75], v[70:71]
	s_nop 0
	v_add_f32_e32 v3, v70, v71
	v_fmamk_f32 v3, v3, 0x3a800000, v164
	v_mul_f32_e32 v70, 0x4f800000, v3
	v_cmp_gt_f32_e32 vcc, s50, v3
	s_nop 1
	v_cndmask_b32_e32 v3, v3, v70, vcc
	v_sqrt_f32_e32 v70, v3
	s_nop 0
	v_add_u32_e32 v71, -1, v70
	v_add_u32_e32 v72, 1, v70
	v_fma_f32 v73, -v71, v70, v3
	v_fma_f32 v74, -v72, v70, v3
	v_cmp_ge_f32_e64 s[8:9], 0, v73
	s_nop 1
	v_cndmask_b32_e64 v70, v70, v71, s[8:9]
	v_cmp_lt_f32_e64 s[8:9], 0, v74
	s_nop 1
	v_cndmask_b32_e64 v70, v70, v72, s[8:9]
	v_mul_f32_e32 v71, 0x37800000, v70
	v_cndmask_b32_e32 v70, v70, v71, vcc
	v_cmp_class_f32_e32 vcc, v3, v162
	s_nop 1
	v_cndmask_b32_e32 v3, v70, v3, vcc
	v_div_scale_f32 v72, s[4:5], v3, v3, 1.0
	v_rcp_f32_e32 v73, v72
	v_div_scale_f32 v74, vcc, 1.0, v3, 1.0
	v_lshl_add_u64 v[70:71], s[22:23], 0, v[86:87]
	v_fma_f32 v75, -v72, v73, 1.0
	v_fmac_f32_e32 v73, v75, v73
	v_mul_f32_e32 v75, v74, v73
	v_fma_f32 v76, -v72, v75, v74
	v_fmac_f32_e32 v75, v76, v73
	v_fma_f32 v72, -v72, v75, v74
	v_div_fmas_f32 v72, v72, v73, v75
	v_div_fixup_f32 v72, v72, v3, 1.0
	v_pk_mul_f32 v[66:67], v[66:67], v[72:73] op_sel_hi:[1,0]
	v_pk_mul_f32 v[68:69], v[68:69], v[72:73] op_sel_hi:[1,0]
	v_pk_mul_f32 v[74:75], v[62:63], v[72:73] op_sel_hi:[1,0]
	v_pk_mul_f32 v[76:77], v[64:65], v[72:73] op_sel_hi:[1,0]
	s_waitcnt vmcnt(3)
	v_pk_fma_f32 v[64:65], v[80:81], s[48:49], v[68:69] op_sel_hi:[1,0,1]
	v_pk_fma_f32 v[62:63], v[78:79], s[48:49], v[66:67] op_sel_hi:[1,0,1]
	s_waitcnt vmcnt(2)
	v_pk_fma_f32 v[68:69], v[84:85], s[48:49], v[76:77] op_sel_hi:[1,0,1]
	v_pk_fma_f32 v[66:67], v[82:83], s[48:49], v[74:75] op_sel_hi:[1,0,1]
	global_store_dwordx4 v[70:71], v[62:65], off
	global_store_dwordx4 v[70:71], v[66:69], off offset:16
	v_add_u32_e32 v70, 0x90, v134
	v_or_b32_e32 v86, 0x200, v86
	v_pk_mul_f32 v[60:61], v[60:61], v[72:73] op_sel_hi:[1,0]
	v_pk_mul_f32 v[58:59], v[58:59], v[72:73] op_sel_hi:[1,0]
	v_ashrrev_i32_e32 v71, 31, v70
	v_lshl_add_u64 v[76:77], s[22:23], 0, v[86:87]
	v_pk_mul_f32 v[78:79], v[56:57], v[72:73] op_sel_hi:[1,0]
	v_pk_mul_f32 v[72:73], v[54:55], v[72:73] op_sel_hi:[1,0]
	v_lshlrev_b64 v[74:75], 6, v[70:71]
	v_lshl_add_u64 v[74:75], s[26:27], 0, v[74:75]
	s_waitcnt vmcnt(3)
	v_pk_fma_f32 v[54:55], v[170:171], s[48:49], v[58:59] op_sel_hi:[1,0,1]
	v_pk_fma_f32 v[56:57], v[172:173], s[48:49], v[60:61] op_sel_hi:[1,0,1]
	s_waitcnt vmcnt(2)
	v_pk_fma_f32 v[58:59], v[174:175], s[48:49], v[72:73] op_sel_hi:[1,0,1]
	v_pk_fma_f32 v[60:61], v[176:177], s[48:49], v[78:79] op_sel_hi:[1,0,1]
	global_store_dwordx4 v[76:77], v[54:57], off
	global_store_dwordx4 v[76:77], v[58:61], off offset:16
	global_load_dwordx4 v[54:57], v[74:75], off offset:32
	global_load_dwordx4 v[58:61], v[74:75], off offset:48
	v_lshlrev_b64 v[62:63], 11, v[70:71]
	v_lshl_add_u64 v[62:63], v[62:63], 0, v[4:5]
	v_lshlrev_b64 v[70:71], 2, v[62:63]
	v_lshl_add_u64 v[72:73], s[76:77], 0, v[70:71]
	global_load_dwordx4 v[62:65], v[72:73], off
	global_load_dwordx4 v[66:69], v[72:73], off offset:16
	global_load_dwordx4 v[170:173], v[72:73], off offset:512
	global_load_dwordx4 v[174:177], v[72:73], off offset:528
	s_waitcnt vmcnt(4)
	v_pk_add_f32 v[56:57], v[56:57], v[60:61]
	v_pk_add_f32 v[54:55], v[54:55], v[58:59]
	s_nop 0
	v_pk_mov_b32 v[58:59], v[54:55], v[56:57] op_sel:[1,0]
	v_mov_b32_e32 v55, v57
	v_pk_add_f32 v[54:55], v[58:59], v[54:55]
	s_nop 0
	v_add_f32_e32 v3, v54, v55
	v_fmamk_f32 v3, v3, 0x3a800000, v164
	v_mul_f32_e32 v54, 0x4f800000, v3
	v_cmp_gt_f32_e32 vcc, s50, v3
	s_nop 1
	v_cndmask_b32_e32 v3, v3, v54, vcc
	v_sqrt_f32_e32 v54, v3
	s_nop 0
	v_add_u32_e32 v55, -1, v54
	v_add_u32_e32 v56, 1, v54
	v_fma_f32 v57, -v55, v54, v3
	v_fma_f32 v58, -v56, v54, v3
	v_cmp_ge_f32_e64 s[8:9], 0, v57
	s_nop 1
	v_cndmask_b32_e64 v54, v54, v55, s[8:9]
	v_cmp_lt_f32_e64 s[8:9], 0, v58
	s_nop 1
	v_cndmask_b32_e64 v54, v54, v56, s[8:9]
	v_mul_f32_e32 v55, 0x37800000, v54
	v_cndmask_b32_e32 v54, v54, v55, vcc
	v_cmp_class_f32_e32 vcc, v3, v162
	s_nop 1
	v_cndmask_b32_e32 v3, v54, v3, vcc
	v_div_scale_f32 v56, s[4:5], v3, v3, 1.0
	v_rcp_f32_e32 v57, v56
	v_div_scale_f32 v58, vcc, 1.0, v3, 1.0
	v_lshl_add_u64 v[54:55], s[22:23], 0, v[70:71]
	v_fma_f32 v59, -v56, v57, 1.0
	v_fmac_f32_e32 v57, v59, v57
	v_mul_f32_e32 v59, v58, v57
	v_fma_f32 v60, -v56, v59, v58
	v_fmac_f32_e32 v59, v60, v57
	v_fma_f32 v56, -v56, v59, v58
	v_div_fmas_f32 v56, v56, v57, v59
	v_div_fixup_f32 v56, v56, v3, 1.0
	v_pk_mul_f32 v[50:51], v[50:51], v[56:57] op_sel_hi:[1,0]
	v_pk_mul_f32 v[52:53], v[52:53], v[56:57] op_sel_hi:[1,0]
	v_pk_mul_f32 v[58:59], v[46:47], v[56:57] op_sel_hi:[1,0]
	v_pk_mul_f32 v[60:61], v[48:49], v[56:57] op_sel_hi:[1,0]
	s_waitcnt vmcnt(3)
	v_pk_fma_f32 v[48:49], v[64:65], s[48:49], v[52:53] op_sel_hi:[1,0,1]
	v_pk_fma_f32 v[46:47], v[62:63], s[48:49], v[50:51] op_sel_hi:[1,0,1]
	s_waitcnt vmcnt(2)
	v_pk_fma_f32 v[52:53], v[68:69], s[48:49], v[60:61] op_sel_hi:[1,0,1]
	v_pk_fma_f32 v[50:51], v[66:67], s[48:49], v[58:59] op_sel_hi:[1,0,1]
	global_store_dwordx4 v[54:55], v[46:49], off
	global_store_dwordx4 v[54:55], v[50:53], off offset:16
	v_add_u32_e32 v54, 0xa0, v134
	v_or_b32_e32 v70, 0x200, v70
	v_pk_mul_f32 v[44:45], v[44:45], v[56:57] op_sel_hi:[1,0]
	v_pk_mul_f32 v[42:43], v[42:43], v[56:57] op_sel_hi:[1,0]
	v_ashrrev_i32_e32 v55, 31, v54
	v_lshl_add_u64 v[60:61], s[22:23], 0, v[70:71]
	v_pk_mul_f32 v[62:63], v[40:41], v[56:57] op_sel_hi:[1,0]
	v_pk_mul_f32 v[56:57], v[38:39], v[56:57] op_sel_hi:[1,0]
	v_lshlrev_b64 v[58:59], 6, v[54:55]
	v_lshl_add_u64 v[58:59], s[26:27], 0, v[58:59]
	s_waitcnt vmcnt(3)
	v_pk_fma_f32 v[38:39], v[170:171], s[48:49], v[42:43] op_sel_hi:[1,0,1]
	v_pk_fma_f32 v[40:41], v[172:173], s[48:49], v[44:45] op_sel_hi:[1,0,1]
	s_waitcnt vmcnt(2)
	v_pk_fma_f32 v[42:43], v[174:175], s[48:49], v[56:57] op_sel_hi:[1,0,1]
	v_pk_fma_f32 v[44:45], v[176:177], s[48:49], v[62:63] op_sel_hi:[1,0,1]
	global_store_dwordx4 v[60:61], v[38:41], off
	global_store_dwordx4 v[60:61], v[42:45], off offset:16
	global_load_dwordx4 v[38:41], v[58:59], off offset:32
	global_load_dwordx4 v[42:45], v[58:59], off offset:48
	v_lshlrev_b64 v[46:47], 11, v[54:55]
	v_lshl_add_u64 v[46:47], v[46:47], 0, v[4:5]
	v_lshlrev_b64 v[54:55], 2, v[46:47]
	v_lshl_add_u64 v[56:57], s[76:77], 0, v[54:55]
	global_load_dwordx4 v[46:49], v[56:57], off
	global_load_dwordx4 v[50:53], v[56:57], off offset:16
	global_load_dwordx4 v[170:173], v[56:57], off offset:512
	global_load_dwordx4 v[174:177], v[56:57], off offset:528
	s_waitcnt vmcnt(4)
	v_pk_add_f32 v[40:41], v[40:41], v[44:45]
	v_pk_add_f32 v[38:39], v[38:39], v[42:43]
	s_nop 0
	v_pk_mov_b32 v[42:43], v[38:39], v[40:41] op_sel:[1,0]
	v_mov_b32_e32 v39, v41
	v_pk_add_f32 v[38:39], v[42:43], v[38:39]
	s_nop 0
	v_add_f32_e32 v3, v38, v39
	v_fmamk_f32 v3, v3, 0x3a800000, v164
	v_mul_f32_e32 v38, 0x4f800000, v3
	v_cmp_gt_f32_e32 vcc, s50, v3
	s_nop 1
	v_cndmask_b32_e32 v3, v3, v38, vcc
	v_sqrt_f32_e32 v38, v3
	s_nop 0
	v_add_u32_e32 v39, -1, v38
	v_add_u32_e32 v40, 1, v38
	v_fma_f32 v41, -v39, v38, v3
	v_fma_f32 v42, -v40, v38, v3
	v_cmp_ge_f32_e64 s[8:9], 0, v41
	s_nop 1
	v_cndmask_b32_e64 v38, v38, v39, s[8:9]
	v_cmp_lt_f32_e64 s[8:9], 0, v42
	s_nop 1
	v_cndmask_b32_e64 v38, v38, v40, s[8:9]
	v_mul_f32_e32 v39, 0x37800000, v38
	v_cndmask_b32_e32 v38, v38, v39, vcc
	v_cmp_class_f32_e32 vcc, v3, v162
	s_nop 1
	v_cndmask_b32_e32 v3, v38, v3, vcc
	v_div_scale_f32 v40, s[4:5], v3, v3, 1.0
	v_rcp_f32_e32 v41, v40
	v_div_scale_f32 v42, vcc, 1.0, v3, 1.0
	v_lshl_add_u64 v[38:39], s[22:23], 0, v[54:55]
	v_fma_f32 v43, -v40, v41, 1.0
	v_fmac_f32_e32 v41, v43, v41
	v_mul_f32_e32 v43, v42, v41
	v_fma_f32 v44, -v40, v43, v42
	v_fmac_f32_e32 v43, v44, v41
	v_fma_f32 v40, -v40, v43, v42
	v_div_fmas_f32 v40, v40, v41, v43
	v_div_fixup_f32 v40, v40, v3, 1.0
	v_pk_mul_f32 v[34:35], v[34:35], v[40:41] op_sel_hi:[1,0]
	v_pk_mul_f32 v[36:37], v[36:37], v[40:41] op_sel_hi:[1,0]
	v_pk_mul_f32 v[42:43], v[30:31], v[40:41] op_sel_hi:[1,0]
	v_pk_mul_f32 v[44:45], v[32:33], v[40:41] op_sel_hi:[1,0]
	s_waitcnt vmcnt(3)
	v_pk_fma_f32 v[32:33], v[48:49], s[48:49], v[36:37] op_sel_hi:[1,0,1]
	v_pk_fma_f32 v[30:31], v[46:47], s[48:49], v[34:35] op_sel_hi:[1,0,1]
	s_waitcnt vmcnt(2)
	v_pk_fma_f32 v[36:37], v[52:53], s[48:49], v[44:45] op_sel_hi:[1,0,1]
	v_pk_fma_f32 v[34:35], v[50:51], s[48:49], v[42:43] op_sel_hi:[1,0,1]
	global_store_dwordx4 v[38:39], v[30:33], off
	global_store_dwordx4 v[38:39], v[34:37], off offset:16
	v_add_u32_e32 v38, 0xb0, v134
	v_or_b32_e32 v54, 0x200, v54
	v_pk_mul_f32 v[28:29], v[28:29], v[40:41] op_sel_hi:[1,0]
	v_pk_mul_f32 v[26:27], v[26:27], v[40:41] op_sel_hi:[1,0]
	v_ashrrev_i32_e32 v39, 31, v38
	v_lshl_add_u64 v[44:45], s[22:23], 0, v[54:55]
	v_pk_mul_f32 v[46:47], v[24:25], v[40:41] op_sel_hi:[1,0]
	v_pk_mul_f32 v[40:41], v[22:23], v[40:41] op_sel_hi:[1,0]
	v_lshlrev_b64 v[42:43], 6, v[38:39]
	v_lshl_add_u64 v[42:43], s[26:27], 0, v[42:43]
	s_waitcnt vmcnt(3)
	v_pk_fma_f32 v[22:23], v[170:171], s[48:49], v[26:27] op_sel_hi:[1,0,1]
	v_pk_fma_f32 v[24:25], v[172:173], s[48:49], v[28:29] op_sel_hi:[1,0,1]
	s_waitcnt vmcnt(2)
	v_pk_fma_f32 v[26:27], v[174:175], s[48:49], v[40:41] op_sel_hi:[1,0,1]
	v_pk_fma_f32 v[28:29], v[176:177], s[48:49], v[46:47] op_sel_hi:[1,0,1]
	global_store_dwordx4 v[44:45], v[22:25], off
	global_store_dwordx4 v[44:45], v[26:29], off offset:16
	global_load_dwordx4 v[22:25], v[42:43], off offset:32
	global_load_dwordx4 v[26:29], v[42:43], off offset:48
	v_lshlrev_b64 v[30:31], 11, v[38:39]
	v_lshl_add_u64 v[4:5], v[30:31], 0, v[4:5]
	v_lshlrev_b64 v[4:5], 2, v[4:5]
	v_lshl_add_u64 v[38:39], s[76:77], 0, v[4:5]
	global_load_dwordx4 v[30:33], v[38:39], off
	global_load_dwordx4 v[34:37], v[38:39], off offset:16
	global_load_dwordx4 v[170:173], v[38:39], off offset:512
	global_load_dwordx4 v[174:177], v[38:39], off offset:528
	s_waitcnt vmcnt(4)
	v_pk_add_f32 v[24:25], v[24:25], v[28:29]
	v_pk_add_f32 v[22:23], v[22:23], v[26:27]
	s_nop 0
	v_pk_mov_b32 v[26:27], v[22:23], v[24:25] op_sel:[1,0]
	v_mov_b32_e32 v23, v25
	v_pk_add_f32 v[22:23], v[26:27], v[22:23]
	s_nop 0
	v_add_f32_e32 v3, v22, v23
	v_fmamk_f32 v3, v3, 0x3a800000, v164
	v_mul_f32_e32 v22, 0x4f800000, v3
	v_cmp_gt_f32_e32 vcc, s50, v3
	s_nop 1
	v_cndmask_b32_e32 v3, v3, v22, vcc
	v_sqrt_f32_e32 v22, v3
	s_nop 0
	v_add_u32_e32 v23, -1, v22
	v_add_u32_e32 v24, 1, v22
	v_fma_f32 v25, -v23, v22, v3
	v_fma_f32 v26, -v24, v22, v3
	v_cmp_ge_f32_e64 s[8:9], 0, v25
	s_nop 1
	v_cndmask_b32_e64 v22, v22, v23, s[8:9]
	v_cmp_lt_f32_e64 s[8:9], 0, v26
	s_nop 1
	v_cndmask_b32_e64 v22, v22, v24, s[8:9]
	v_mul_f32_e32 v23, 0x37800000, v22
	v_cndmask_b32_e32 v22, v22, v23, vcc
	v_cmp_class_f32_e32 vcc, v3, v162
	s_nop 1
	v_cndmask_b32_e32 v3, v22, v3, vcc
	v_div_scale_f32 v24, s[4:5], v3, v3, 1.0
	v_rcp_f32_e32 v25, v24
	v_div_scale_f32 v26, vcc, 1.0, v3, 1.0
	v_lshl_add_u64 v[22:23], s[22:23], 0, v[4:5]
	v_fma_f32 v27, -v24, v25, 1.0
	v_fmac_f32_e32 v25, v27, v25
	v_mul_f32_e32 v27, v26, v25
	v_fma_f32 v28, -v24, v27, v26
	v_fmac_f32_e32 v27, v28, v25
	v_fma_f32 v24, -v24, v27, v26
	v_div_fmas_f32 v24, v24, v25, v27
	v_div_fixup_f32 v24, v24, v3, 1.0
	v_pk_mul_f32 v[18:19], v[18:19], v[24:25] op_sel_hi:[1,0]
	v_pk_mul_f32 v[20:21], v[20:21], v[24:25] op_sel_hi:[1,0]
	v_pk_mul_f32 v[26:27], v[14:15], v[24:25] op_sel_hi:[1,0]
	v_pk_mul_f32 v[28:29], v[16:17], v[24:25] op_sel_hi:[1,0]
	s_waitcnt vmcnt(3)
	v_pk_fma_f32 v[16:17], v[32:33], s[48:49], v[20:21] op_sel_hi:[1,0,1]
	v_pk_fma_f32 v[14:15], v[30:31], s[48:49], v[18:19] op_sel_hi:[1,0,1]
	s_waitcnt vmcnt(2)
	v_pk_fma_f32 v[20:21], v[36:37], s[48:49], v[28:29] op_sel_hi:[1,0,1]
	v_pk_fma_f32 v[18:19], v[34:35], s[48:49], v[26:27] op_sel_hi:[1,0,1]
	global_store_dwordx4 v[22:23], v[14:17], off
	global_store_dwordx4 v[22:23], v[18:21], off offset:16
	v_or_b32_e32 v4, 0x200, v4
	v_lshl_add_u64 v[22:23], s[22:23], 0, v[4:5]
	v_pk_mul_f32 v[12:13], v[12:13], v[24:25] op_sel_hi:[1,0]
	v_pk_mul_f32 v[4:5], v[10:11], v[24:25] op_sel_hi:[1,0]
	v_pk_mul_f32 v[10:11], v[8:9], v[24:25] op_sel_hi:[1,0]
	v_pk_mul_f32 v[8:9], v[6:7], v[24:25] op_sel_hi:[1,0]
	s_andn2_b64 vcc, exec, s[6:7]
	s_mov_b64 s[4:5], -1
	s_waitcnt vmcnt(3)
	v_pk_fma_f32 v[4:5], v[170:171], s[48:49], v[4:5] op_sel_hi:[1,0,1]
	v_pk_fma_f32 v[6:7], v[172:173], s[48:49], v[12:13] op_sel_hi:[1,0,1]
	s_waitcnt vmcnt(2)
	v_pk_fma_f32 v[8:9], v[174:175], s[48:49], v[8:9] op_sel_hi:[1,0,1]
	v_pk_fma_f32 v[10:11], v[176:177], s[48:49], v[10:11] op_sel_hi:[1,0,1]
	global_store_dwordx4 v[22:23], v[4:7], off
	global_store_dwordx4 v[22:23], v[8:11], off offset:16
	s_cbranch_vccnz .LBB0_849
	s_andn2_b64 vcc, exec, s[20:21]
	s_cbranch_vccnz .LBB0_848
	s_barrier
	s_branch .LBB0_848
